# attention: static s_setprio 1 for the map-1 (trailing) waves of each SIMD pair; RWKV packed-f32 step loop + pipelined helper loads
# speedup vs baseline: 1.0020x; 1.0004x over previous
; #define otid() otid_(wv)
; __device__ __forceinline__ void phase_mixer(PC p, int wv, int L, LAS unsigned char* lds) {
;     ...
;     for (;;) {
;         __syncthreads();
;         if (otid() == 0) *slot = (int)atomicAdd(p->ctr + L * 16, 1u);
;         __syncthreads();
;         const int it = *slot;
;         if (it >= 128 + 16 + 512) break;
.LBB0_286:
	s_setprio 0
	s_waitcnt vmcnt(5)
	v_mov_b32_e32 v0, v137
	s_barrier
	s_nop 0
	v_mbcnt_lo_u32_b32 v0, -1, v0
	v_mbcnt_hi_u32_b32 v0, -1, v0
	v_cmp_eq_u32_e32 vcc, s73, v0
	s_and_saveexec_b64 s[4:5], vcc
	s_cbranch_execz .LBB0_290
	s_mov_b64 s[10:11], exec
	v_mbcnt_lo_u32_b32 v0, s10, 0
	v_mbcnt_hi_u32_b32 v0, s11, v0
	v_cmp_eq_u32_e32 vcc, 0, v0
	s_and_saveexec_b64 s[8:9], vcc
	s_cbranch_execz .LBB0_289
	s_load_dwordx2 s[12:13], s[52:53], 0x1d0
	s_bcnt1_i32_b64 s10, s[10:11]
	v_mov_b32_e32 v1, s10
	s_waitcnt lgkmcnt(0)
	global_atomic_add v1, v137, v1, s[12:13] sc0

; __device__ __forceinline__ float wave_sum(float v) { v = allreduce16(v); v += swz16(v); return sum32(v); }
; __device__ __forceinline__ void attn_item(PC p, int wv, int L, int item, LAS unsigned char* lds) {
;     ...
;     float lam, M2; const float lam_init = 0.8f - 0.6f * __expf(-0.3f * (float)L);
;     {
;         const float* lp = p->a_lambda + L * 256;
;         const float s1 = wave_sum(lp[lane] * lp[64 + lane]), s2 = wave_sum(lp[128 + lane] * lp[192 + lane]);
;         lam = __expf(s1) - __expf(s2) + lam_init;
;         const float gq = wave_max(fabsf(p->a_qnorm[L * 64 + lane])), gk = wave_max(fabsf(p->a_knorm[L * 64 + lane]));
;         const float tb = wave_max(fabsf(p->rel_bias[(lane & 31) * 4 + h]));
;         M2 = 8.0f * LOG2E * gq * gk + LOG2E * tb;
;     }
;     if (tid < 257) lut[tid] = p->rel_bias[t5_bucket(tid - 128) * 4 + h] * LOG2E - M2;
; __device__ __forceinline__ void phase_mixer(PC p, int wv, int L, LAS unsigned char* lds) {
;     ...
;         __syncthreads();
;         const int it = *slot;
;         if (it >= 128 + 16 + 512) break;
;         if (it < 128) rwkv_item(p, wv, L, it, lds);
;         else if (it < 144) hgrn_item(p, wv, L, it - 128, lds);
;         else attn_item(p, wv, L, it - 144, lds);
.LBB0_290:
	s_or_b64 exec, exec, s[4:5]
	s_waitcnt lgkmcnt(0)
	s_barrier
	ds_read_b32 v0, v152
	s_movk_i32 s4, 0x28f
	s_waitcnt lgkmcnt(0)
	v_cmp_lt_i32_e32 vcc, s4, v0
	v_readfirstlane_b32 s90, v0
	s_mov_b64 s[4:5], -1
	s_cbranch_vccnz .LBB0_285
	s_cmpk_gt_i32 s90, 0x7f
	s_cbranch_scc0 .LBB0_319
	s_cmpk_gt_u32 s90, 0x8f
	s_cbranch_scc0 .LBB0_320
	s_cmpk_lt_u32 s3, 0x100
	s_cbranch_scc1 .Lat_prio_0
	s_setprio 1
.Lat_prio_0:
	v_mov_b32_e32 v0, v137
	s_load_dwordx8 s[8:15], s[52:53], 0x28
	v_mbcnt_lo_u32_b32 v0, -1, v0
	s_add_i32 s17, s90, 0xffffff70
	v_mbcnt_hi_u32_b32 v56, -1, v0
	v_and_b32_e32 v0, 63, v56
	s_bfe_u32 s16, s17, 0x20006
	v_and_b32_e32 v183, 31, v56
	v_lshlrev_b32_e32 v1, 2, v0
	s_lshl_b32 s4, s16, 2
	s_waitcnt lgkmcnt(0)
	global_load_dword v2, v1, s[14:15]
	global_load_dword v3, v1, s[14:15] offset:256
	global_load_dword v4, v1, s[14:15] offset:512
	global_load_dword v5, v1, s[14:15] offset:768
	global_load_dword v6, v1, s[10:11]
	global_load_dword v7, v1, s[12:13]
	v_lshl_or_b32 v1, v183, 4, s4
	global_load_dword v8, v1, s[8:9]
	s_load_dwordx2 s[4:5], s[52:53], 0x108
	s_movk_i32 s10, 0x101
	v_add_u32_e32 v1, s72, v56
	v_cmp_gt_i32_e32 vcc, s10, v1
	s_waitcnt vmcnt(5)
	v_mul_f32_e32 v9, v2, v3
	s_nop 1
	v_mov_b32_dpp v9, v9 quad_perm:[1,0,3,2] row_mask:0xf bank_mask:0xf bound_ctrl:1
	s_waitcnt vmcnt(3)
	v_mul_f32_e32 v10, v4, v5
	s_waitcnt vmcnt(2)
	v_and_b32_e32 v11, 0x7fffffff, v6
	s_waitcnt vmcnt(1)
	v_and_b32_e32 v12, 0x7fffffff, v7
	v_mov_b32_dpp v10, v10 quad_perm:[1,0,3,2] row_mask:0xf bank_mask:0xf bound_ctrl:1
	s_waitcnt vmcnt(0)
	v_and_b32_e32 v13, 0x7fffffff, v8
	v_mov_b32_dpp v11, v11 quad_perm:[1,0,3,2] row_mask:0xf bank_mask:0xf bound_ctrl:1
	v_mov_b32_dpp v12, v12 quad_perm:[1,0,3,2] row_mask:0xf bank_mask:0xf bound_ctrl:1
	v_mov_b32_dpp v13, v13 quad_perm:[1,0,3,2] row_mask:0xf bank_mask:0xf bound_ctrl:1
	v_max_f32_e64 v6, |v6|, |v6|
	v_max_f32_e64 v7, |v7|, |v7|
	v_max_f32_e64 v8, |v8|, |v8|
	v_fmac_f32_e32 v9, v2, v3
	v_fmac_f32_e32 v10, v4, v5
	v_max_f32_e32 v2, v11, v11
	v_max_f32_e32 v3, v12, v12
	v_max_f32_e32 v4, v13, v13
	v_add_f32_dpp v5, v9, v9 quad_perm:[2,3,0,1] row_mask:0xf bank_mask:0xf bound_ctrl:1
	v_add_f32_dpp v9, v10, v10 quad_perm:[2,3,0,1] row_mask:0xf bank_mask:0xf bound_ctrl:1
	v_max_f32_e32 v2, v6, v2
	v_max_f32_e32 v3, v7, v3
	v_max_f32_e32 v4, v8, v4
	v_add_f32_dpp v5, v5, v5 row_half_mirror row_mask:0xf bank_mask:0xf bound_ctrl:1
	v_add_f32_dpp v6, v9, v9 row_half_mirror row_mask:0xf bank_mask:0xf bound_ctrl:1
	v_mov_b32_dpp v7, v2 quad_perm:[2,3,0,1] row_mask:0xf bank_mask:0xf bound_ctrl:1
	v_mov_b32_dpp v8, v3 quad_perm:[2,3,0,1] row_mask:0xf bank_mask:0xf bound_ctrl:1
	v_mov_b32_dpp v9, v4 quad_perm:[2,3,0,1] row_mask:0xf bank_mask:0xf bound_ctrl:1
	v_add_f32_dpp v5, v5, v5 row_mirror row_mask:0xf bank_mask:0xf bound_ctrl:1
	v_add_f32_dpp v6, v6, v6 row_mirror row_mask:0xf bank_mask:0xf bound_ctrl:1
	v_max_f32_e32 v7, v7, v7
	v_max_f32_e32 v8, v8, v8
	v_max_f32_e32 v9, v9, v9
	ds_swizzle_b32 v10, v5 offset:swizzle(SWAP,16)
	ds_swizzle_b32 v11, v6 offset:swizzle(SWAP,16)
	v_max_f32_e32 v2, v2, v7
	v_max_f32_e32 v3, v3, v8
	v_max_f32_e32 v4, v4, v9
	v_mov_b32_dpp v7, v2 row_half_mirror row_mask:0xf bank_mask:0xf bound_ctrl:1
	v_mov_b32_dpp v8, v3 row_half_mirror row_mask:0xf bank_mask:0xf bound_ctrl:1
	v_mov_b32_dpp v9, v4 row_half_mirror row_mask:0xf bank_mask:0xf bound_ctrl:1
	v_max_f32_e32 v7, v7, v7
	v_max_f32_e32 v8, v8, v8
	v_max_f32_e32 v9, v9, v9
	v_max_f32_e32 v2, v2, v7
	v_max_f32_e32 v3, v3, v8
	v_max_f32_e32 v4, v4, v9
	v_mov_b32_dpp v7, v2 row_mirror row_mask:0xf bank_mask:0xf bound_ctrl:1
	v_mov_b32_dpp v8, v3 row_mirror row_mask:0xf bank_mask:0xf bound_ctrl:1
	v_mov_b32_dpp v9, v4 row_mirror row_mask:0xf bank_mask:0xf bound_ctrl:1
	s_waitcnt lgkmcnt(0)
	v_add_f32_e32 v184, v5, v10
	v_add_f32_e32 v185, v6, v11
	v_max_f32_e32 v5, v7, v7
	v_max_f32_e32 v6, v8, v8
	v_max_f32_e32 v7, v9, v9
	v_max_f32_e32 v2, v2, v5
	v_max_f32_e32 v3, v3, v6
	v_max_f32_e32 v5, v4, v7
	ds_swizzle_b32 v4, v2 offset:swizzle(SWAP,16)
	ds_swizzle_b32 v6, v3 offset:swizzle(SWAP,16)
	ds_swizzle_b32 v7, v5 offset:swizzle(SWAP,16)
	v_mov_b32_e32 v186, v184
	v_mov_b32_e32 v187, v185
	s_waitcnt lgkmcnt(2)
	v_max_f32_e32 v4, v4, v4
	s_waitcnt lgkmcnt(1)
	v_max_f32_e32 v6, v6, v6
	s_waitcnt lgkmcnt(0)
	v_max_f32_e32 v7, v7, v7
	v_max_f32_e32 v2, v2, v4
	v_max_f32_e32 v4, v3, v6
	v_max_f32_e32 v6, v5, v7
	v_mov_b32_e32 v3, v2
	v_mov_b32_e32 v5, v4
	v_mov_b32_e32 v7, v6
	v_permlane32_swap_b32_e32 v184, v186
	v_permlane32_swap_b32_e32 v185, v187
	v_permlane32_swap_b32_e32 v2, v3
	v_permlane32_swap_b32_e32 v4, v5
	v_permlane32_swap_b32_e32 v6, v7
	s_and_saveexec_b64 s[10:11], vcc
	s_cbranch_execz .LBB0_297
	v_add_u32_e32 v8, 0xffffff80, v1
	v_sub_u32_e32 v9, 0x80, v1
	v_max_i32_e32 v8, v8, v9
	v_cmp_lt_u32_e32 vcc, 7, v8
	s_and_saveexec_b64 s[12:13], vcc
	s_cbranch_execz .LBB0_296
	v_cvt_f32_u32_e32 v8, v8
	s_mov_b32 s14, 0x3f317217
	s_mov_b32 s15, 0x7f800000
	v_mul_f32_e32 v8, 0x3e000000, v8
	v_cmp_gt_f32_e32 vcc, s83, v8
	s_nop 1
	v_cndmask_b32_e64 v9, 0, 32, vcc
	v_ldexp_f32 v8, v8, v9
	v_log_f32_e32 v8, v8
	v_cndmask_b32_e32 v9, 0, v154, vcc
	v_mul_f32_e32 v10, 0x3f317217, v8
	v_fma_f32 v10, v8, s14, -v10
	v_fmac_f32_e32 v10, 0x3377d1cf, v8
	v_fmac_f32_e32 v10, 0x3f317217, v8
	v_cmp_lt_f32_e64 vcc, |v8|, s15
	s_nop 1
	v_cndmask_b32_e32 v8, v8, v10, vcc
	v_sub_f32_e32 v8, v8, v9
	v_div_scale_f32 v9, s[14:15], s84, s84, v8
	v_rcp_f32_e32 v10, v9
	v_div_scale_f32 v11, vcc, v8, s84, v8
	v_fma_f32 v12, -v9, v10, 1.0
	v_fmac_f32_e32 v10, v12, v10
	v_mul_f32_e32 v12, v11, v10
	v_fma_f32 v13, -v9, v12, v11
	v_fmac_f32_e32 v12, v13, v10
	v_fma_f32 v9, -v9, v12, v11
	v_div_fmas_f32 v9, v9, v10, v12
	v_div_fixup_f32 v8, v9, s84, v8
	v_mul_f32_e32 v8, 0x41000000, v8
	v_cvt_i32_f32_e32 v8, v8
	v_min_i32_e32 v8, 7, v8
	v_add_u32_e32 v8, 8, v8

; #define otid() otid_(wv)
; __device__ __forceinline__ void phase_mixer(PC p, int wv, int L, LAS unsigned char* lds) {
;     ...
;     for (;;) {
;         __syncthreads();
;         if (otid() == 0) *slot = (int)atomicAdd(p->ctr + L * 16, 1u);
;         __syncthreads();
;         const int it = *slot;
;         if (it >= 128 + 16 + 512) break;
.LBB0_961:
	s_setprio 0
	s_waitcnt vmcnt(5)
	v_mov_b32_e32 v0, v137
	s_barrier
	s_nop 0
	v_mbcnt_lo_u32_b32 v0, -1, v0
	v_mbcnt_hi_u32_b32 v0, -1, v0
	v_cmp_eq_u32_e32 vcc, s73, v0
	s_and_saveexec_b64 s[6:7], vcc
	s_cbranch_execz .LBB0_965
	s_mov_b64 s[10:11], exec
	v_mbcnt_lo_u32_b32 v0, s10, 0
	v_mbcnt_hi_u32_b32 v0, s11, v0
	v_cmp_eq_u32_e32 vcc, 0, v0
	s_and_saveexec_b64 s[8:9], vcc
	s_cbranch_execz .LBB0_964
	s_load_dwordx2 s[12:13], s[56:57], 0x1d0
	s_bcnt1_i32_b64 s10, s[10:11]
	v_mov_b32_e32 v1, s10
	s_waitcnt lgkmcnt(0)
	global_atomic_add v1, v137, v1, s[12:13] offset:64 sc0

; __device__ __forceinline__ float wave_sum(float v) { v = allreduce16(v); v += swz16(v); return sum32(v); }
; __device__ __forceinline__ void attn_item(PC p, int wv, int L, int item, LAS unsigned char* lds) {
;     ...
;     float lam, M2; const float lam_init = 0.8f - 0.6f * __expf(-0.3f * (float)L);
;     {
;         const float* lp = p->a_lambda + L * 256;
;         const float s1 = wave_sum(lp[lane] * lp[64 + lane]), s2 = wave_sum(lp[128 + lane] * lp[192 + lane]);
;         lam = __expf(s1) - __expf(s2) + lam_init;
;         const float gq = wave_max(fabsf(p->a_qnorm[L * 64 + lane])), gk = wave_max(fabsf(p->a_knorm[L * 64 + lane]));
;         const float tb = wave_max(fabsf(p->rel_bias[(lane & 31) * 4 + h]));
;         M2 = 8.0f * LOG2E * gq * gk + LOG2E * tb;
;     }
;     if (tid < 257) lut[tid] = p->rel_bias[t5_bucket(tid - 128) * 4 + h] * LOG2E - M2;
; __device__ __forceinline__ void phase_mixer(PC p, int wv, int L, LAS unsigned char* lds) {
;     ...
;         __syncthreads();
;         const int it = *slot;
;         if (it >= 128 + 16 + 512) break;
;         if (it < 128) rwkv_item(p, wv, L, it, lds);
;         else if (it < 144) hgrn_item(p, wv, L, it - 128, lds);
;         else attn_item(p, wv, L, it - 144, lds);
.LBB0_965:
	s_or_b64 exec, exec, s[6:7]
	s_waitcnt lgkmcnt(0)
	s_barrier
	ds_read_b32 v0, v154
	s_movk_i32 s6, 0x28f
	s_waitcnt lgkmcnt(0)
	v_cmp_lt_i32_e32 vcc, s6, v0
	v_readfirstlane_b32 s88, v0
	s_mov_b64 s[6:7], -1
	s_cbranch_vccnz .LBB0_960
	s_cmpk_gt_i32 s88, 0x7f
	s_cbranch_scc0 .LBB0_994
	s_cmpk_gt_u32 s88, 0x8f
	s_cbranch_scc0 .LBB0_995
	s_cmpk_lt_u32 s3, 0x100
	s_cbranch_scc1 .Lat_prio_1
	s_setprio 1
.Lat_prio_1:
	v_mov_b32_e32 v0, v137
	s_load_dwordx8 s[8:15], s[56:57], 0x28
	v_mbcnt_lo_u32_b32 v0, -1, v0
	s_add_i32 s17, s88, 0xffffff70
	v_mbcnt_hi_u32_b32 v56, -1, v0
	v_and_b32_e32 v0, 63, v56
	s_bfe_u32 s16, s17, 0x20006
	v_and_b32_e32 v185, 31, v56
	v_lshlrev_b32_e32 v1, 2, v0
	s_lshl_b32 s6, s16, 2
	s_waitcnt lgkmcnt(0)
	global_load_dword v2, v1, s[14:15] offset:1024
	global_load_dword v3, v1, s[14:15] offset:1280
	global_load_dword v4, v1, s[14:15] offset:1536
	global_load_dword v5, v1, s[14:15] offset:1792
	global_load_dword v6, v1, s[10:11] offset:256
	global_load_dword v7, v1, s[12:13] offset:256
	v_lshl_or_b32 v1, v185, 4, s6
	global_load_dword v8, v1, s[8:9]
	s_load_dwordx2 s[6:7], s[56:57], 0x108
	s_movk_i32 s10, 0x101
	v_add_u32_e32 v1, s72, v56
	v_cmp_gt_i32_e32 vcc, s10, v1
	s_waitcnt vmcnt(5)
	v_mul_f32_e32 v9, v2, v3
	s_nop 1
	v_mov_b32_dpp v9, v9 quad_perm:[1,0,3,2] row_mask:0xf bank_mask:0xf bound_ctrl:1
	s_waitcnt vmcnt(3)
	v_mul_f32_e32 v10, v4, v5
	s_waitcnt vmcnt(2)
	v_and_b32_e32 v11, 0x7fffffff, v6
	s_waitcnt vmcnt(1)
	v_and_b32_e32 v12, 0x7fffffff, v7
	v_mov_b32_dpp v10, v10 quad_perm:[1,0,3,2] row_mask:0xf bank_mask:0xf bound_ctrl:1
	s_waitcnt vmcnt(0)
	v_and_b32_e32 v13, 0x7fffffff, v8
	v_mov_b32_dpp v11, v11 quad_perm:[1,0,3,2] row_mask:0xf bank_mask:0xf bound_ctrl:1
	v_mov_b32_dpp v12, v12 quad_perm:[1,0,3,2] row_mask:0xf bank_mask:0xf bound_ctrl:1
	v_mov_b32_dpp v13, v13 quad_perm:[1,0,3,2] row_mask:0xf bank_mask:0xf bound_ctrl:1
	v_max_f32_e64 v6, |v6|, |v6|
	v_max_f32_e64 v7, |v7|, |v7|
	v_max_f32_e64 v8, |v8|, |v8|
	v_fmac_f32_e32 v9, v2, v3
	v_fmac_f32_e32 v10, v4, v5
	v_max_f32_e32 v2, v11, v11
	v_max_f32_e32 v3, v12, v12
	v_max_f32_e32 v4, v13, v13
	v_add_f32_dpp v5, v9, v9 quad_perm:[2,3,0,1] row_mask:0xf bank_mask:0xf bound_ctrl:1
	v_add_f32_dpp v9, v10, v10 quad_perm:[2,3,0,1] row_mask:0xf bank_mask:0xf bound_ctrl:1
	v_max_f32_e32 v2, v6, v2
	v_max_f32_e32 v3, v7, v3
	v_max_f32_e32 v4, v8, v4
	v_add_f32_dpp v5, v5, v5 row_half_mirror row_mask:0xf bank_mask:0xf bound_ctrl:1
	v_add_f32_dpp v6, v9, v9 row_half_mirror row_mask:0xf bank_mask:0xf bound_ctrl:1
	v_mov_b32_dpp v7, v2 quad_perm:[2,3,0,1] row_mask:0xf bank_mask:0xf bound_ctrl:1
	v_mov_b32_dpp v8, v3 quad_perm:[2,3,0,1] row_mask:0xf bank_mask:0xf bound_ctrl:1
	v_mov_b32_dpp v9, v4 quad_perm:[2,3,0,1] row_mask:0xf bank_mask:0xf bound_ctrl:1
	v_add_f32_dpp v5, v5, v5 row_mirror row_mask:0xf bank_mask:0xf bound_ctrl:1
	v_add_f32_dpp v6, v6, v6 row_mirror row_mask:0xf bank_mask:0xf bound_ctrl:1
	v_max_f32_e32 v7, v7, v7
	v_max_f32_e32 v8, v8, v8
	v_max_f32_e32 v9, v9, v9
	ds_swizzle_b32 v10, v5 offset:swizzle(SWAP,16)
	ds_swizzle_b32 v11, v6 offset:swizzle(SWAP,16)
	v_max_f32_e32 v2, v2, v7
	v_max_f32_e32 v3, v3, v8
	v_max_f32_e32 v4, v4, v9
	v_mov_b32_dpp v7, v2 row_half_mirror row_mask:0xf bank_mask:0xf bound_ctrl:1
	v_mov_b32_dpp v8, v3 row_half_mirror row_mask:0xf bank_mask:0xf bound_ctrl:1
	v_mov_b32_dpp v9, v4 row_half_mirror row_mask:0xf bank_mask:0xf bound_ctrl:1
	v_max_f32_e32 v7, v7, v7
	v_max_f32_e32 v8, v8, v8
	v_max_f32_e32 v9, v9, v9
	v_max_f32_e32 v2, v2, v7
	v_max_f32_e32 v3, v3, v8
	v_max_f32_e32 v4, v4, v9
	v_mov_b32_dpp v7, v2 row_mirror row_mask:0xf bank_mask:0xf bound_ctrl:1
	v_mov_b32_dpp v8, v3 row_mirror row_mask:0xf bank_mask:0xf bound_ctrl:1
	v_mov_b32_dpp v9, v4 row_mirror row_mask:0xf bank_mask:0xf bound_ctrl:1
	s_waitcnt lgkmcnt(0)
	v_add_f32_e32 v186, v5, v10
	v_add_f32_e32 v187, v6, v11
	v_max_f32_e32 v5, v7, v7
	v_max_f32_e32 v6, v8, v8
	v_max_f32_e32 v7, v9, v9
	v_max_f32_e32 v2, v2, v5
	v_max_f32_e32 v3, v3, v6
	v_max_f32_e32 v5, v4, v7
	ds_swizzle_b32 v4, v2 offset:swizzle(SWAP,16)
	ds_swizzle_b32 v6, v3 offset:swizzle(SWAP,16)
	ds_swizzle_b32 v7, v5 offset:swizzle(SWAP,16)
	v_mov_b32_e32 v188, v186
	v_mov_b32_e32 v189, v187
	s_waitcnt lgkmcnt(2)
	v_max_f32_e32 v4, v4, v4
	s_waitcnt lgkmcnt(1)
	v_max_f32_e32 v6, v6, v6
	s_waitcnt lgkmcnt(0)
	v_max_f32_e32 v7, v7, v7
	v_max_f32_e32 v2, v2, v4
	v_max_f32_e32 v4, v3, v6
	v_max_f32_e32 v6, v5, v7
	v_mov_b32_e32 v3, v2
	v_mov_b32_e32 v5, v4
	v_mov_b32_e32 v7, v6
	v_permlane32_swap_b32_e32 v186, v188
	v_permlane32_swap_b32_e32 v187, v189
	v_permlane32_swap_b32_e32 v2, v3
	v_permlane32_swap_b32_e32 v4, v5
	v_permlane32_swap_b32_e32 v6, v7
	s_and_saveexec_b64 s[10:11], vcc
	s_cbranch_execz .LBB0_972
	v_add_u32_e32 v8, 0xffffff80, v1
	v_sub_u32_e32 v9, 0x80, v1
	v_max_i32_e32 v8, v8, v9
	v_cmp_lt_u32_e32 vcc, 7, v8
	s_and_saveexec_b64 s[12:13], vcc
	s_cbranch_execz .LBB0_971
	v_cvt_f32_u32_e32 v8, v8
	s_mov_b32 s14, 0x3f317217
	s_mov_b32 s15, 0x7f800000
	v_mul_f32_e32 v8, 0x3e000000, v8
	v_cmp_gt_f32_e32 vcc, s53, v8
	s_nop 1
	v_cndmask_b32_e64 v9, 0, 32, vcc
	v_ldexp_f32 v8, v8, v9
	v_log_f32_e32 v8, v8
	v_cndmask_b32_e32 v9, 0, v156, vcc
	v_mul_f32_e32 v10, 0x3f317217, v8
	v_fma_f32 v10, v8, s14, -v10
	v_fmac_f32_e32 v10, 0x3377d1cf, v8
	v_fmac_f32_e32 v10, 0x3f317217, v8
	v_cmp_lt_f32_e64 vcc, |v8|, s15
	s_nop 1
	v_cndmask_b32_e32 v8, v8, v10, vcc
	v_sub_f32_e32 v8, v8, v9
	v_div_scale_f32 v9, s[14:15], s54, s54, v8
	v_rcp_f32_e32 v10, v9
	v_div_scale_f32 v11, vcc, v8, s54, v8
	v_fma_f32 v12, -v9, v10, 1.0
	v_fmac_f32_e32 v10, v12, v10
	v_mul_f32_e32 v12, v11, v10
	v_fma_f32 v13, -v9, v12, v11
	v_fmac_f32_e32 v12, v13, v10
	v_fma_f32 v9, -v9, v12, v11
	v_div_fmas_f32 v9, v9, v10, v12
	v_div_fixup_f32 v8, v9, s54, v8
	v_mul_f32_e32 v8, 0x41000000, v8
	v_cvt_i32_f32_e32 v8, v8
	v_min_i32_e32 v8, 7, v8
	v_add_u32_e32 v8, 8, v8
